# weight-conversion loops: norm gains applied after the LDS transpose (2 wide gain loads per item instead of 32 serialized ones); FFN2 conversion items rebalanced toward workgroups without a GEMM tile
# speedup vs baseline: 1.0326x; 1.0095x over previous
; #define LAS __attribute__((address_space(3)))
; __device__ __forceinline__ void tr_item(const float* __restrict__ W, int K, int Nsrc, int col0, int nvalid, const float* __restrict__ gain, bf16_t* WT, int drow0, int k0, LAS float* scr, int lane) {
;     float v[32];
; #pragma unroll
;     for (int i = 0; i < 32; ++i) { const int kk = 2 * i + (lane >> 5), n = lane & 31; v[i] = 0.f; if (n < nvalid) v[i] = W[(size_t)(k0 + kk) * Nsrc + col0 + n]; }
; #pragma unroll
;     for (int i = 0; i < 32; ++i) { const int kk = 2 * i + (lane >> 5), n = lane & 31; float x = v[i]; if (gain) x *= gain[k0 + kk]; scr[kk * 33 + n] = x; }
; __device__ __forceinline__ void conv_job(int kind, const float* W, const float* W2, int K, int Nsrc, int Ndst, const float* gain, bf16_t* WT, LAS float* scr, int gw, int NGW, int lane) {
;     const int nb = Ndst / 32, nitems = (K / 64) * nb;
;     for (int it = gw; it < nitems; it += NGW) {
;         const int kb = it / nb, db = it % nb, d0 = db * 32, k0 = kb * 64; const float* src = W; int col0 = d0, nvalid = 32;
;         if (kind == 1) { const int t = d0 >> 8; int r = d0 & 255; if (r >= 128) { src = W2; r -= 128; } col0 = t * 128 + r; }
;         else if (kind == 2) { if (d0 < 7168) col0 = d0; else if (d0 < 11264) col0 = d0 + 16; else if (d0 == 11264) { col0 = 7168; nvalid = 16; } else { col0 = 0; nvalid = 0; } }
;         tr_item(src, K, Nsrc, col0, nvalid, gain, WT, d0, k0, scr, lane);
.LBB0_5:
	s_or_b64 exec, exec, s[0:1]
	s_lshl_b32 s62, s69, 3
	s_cmp_lt_i32 s64, 1
	s_cselect_b64 s[12:13], -1, 0
	s_cmp_gt_i32 s65, 0
	s_cselect_b64 s[0:1], -1, 0
	s_and_b64 s[0:1], s[12:13], s[0:1]
	s_andn2_b64 vcc, exec, s[0:1]
	s_mul_i32 s34, s62, 0x2c000
	s_cbranch_vccnz .LBB0_280
	v_readlane_b32 s4, v253, 0
	v_readlane_b32 s5, v253, 1
	s_load_dwordx2 s[0:1], s[4:5], 0xd8
	s_mov_b32 s16, 0
	s_ashr_i32 s17, s16, 31
	v_mov_b32_e32 v34, v205
	s_waitcnt lgkmcnt(0)
	s_add_u32 s14, s0, s16
	s_addc_u32 s15, s1, s17
	v_readfirstlane_b32 s0, v34
	s_ashr_i32 s22, s0, 6
	s_lshl_b32 s23, s66, 3
	s_mul_i32 s0, s22, 0x2200
	s_add_i32 s2, s22, s23
	s_add_i32 s24, s0, 0
	s_lshl_b64 s[0:1], s[16:17], 3
	s_add_u32 s18, s4, s0
	v_and_b32_e32 v1, 63, v34
	s_addc_u32 s19, s5, s1
	s_cmpk_gt_i32 s2, 0x2bff
	v_and_b32_e32 v4, 31, v34
	v_lshrrev_b32_e32 v2, 5, v1
	v_lshrrev_b32_e32 v28, 3, v1
	v_lshlrev_b32_e32 v36, 3, v1
	s_cbranch_scc1 .LBB0_41
	s_load_dwordx4 s[8:11], s[18:19], 0x10
	s_load_dwordx2 s[0:1], s[18:19], 0x20
	s_movk_i32 s3, 0x84
	v_mov_b32_e32 v3, 0x210
	v_mad_u32_u24 v12, v2, s3, v3
	v_mov_b32_e32 v3, 0x420
	v_mad_u32_u24 v13, v2, s3, v3
	v_mov_b32_e32 v3, 0x630
	v_mad_u32_u24 v14, v2, s3, v3
	v_mov_b32_e32 v3, 0x840
	s_waitcnt lgkmcnt(0)
	s_cmp_lg_u64 s[8:9], 0
	v_mad_u32_u24 v15, v2, s3, v3
	v_and_b32_e32 v3, 56, v36
	v_lshlrev_b32_e32 v153, 2, v3
	v_mov_b32_e32 v7, 0
	s_cselect_b64 s[4:5], -1, 0
	v_lshlrev_b32_e32 v6, 1, v3
	v_lshl_add_u32 v10, v4, 2, s24
	v_mul_u32_u24_e32 v11, 0x84, v2
	v_mul_u32_u24_e32 v5, 0x84, v3
	v_lshl_add_u64 v[8:9], s[14:15], 0, v[6:7]
	s_mov_b64 s[6:7], 0x14300000
	v_lshlrev_b32_e32 v3, 2, v28
	v_cndmask_b32_e64 v16, 0, 1, s[4:5]
	v_lshl_add_u64 v[8:9], v[8:9], 0, s[6:7]
	v_add3_u32 v5, s24, v5, v3
	v_mov_b32_e32 v3, v7
	s_lshl_b32 s3, s2, 5
	s_lshl_b32 s25, s62, 5
	s_lshl_b32 s26, s2, 4
	s_lshl_b32 s27, s62, 4
	v_lshlrev_b32_e32 v6, 2, v4
	s_movk_i32 s28, 0x5800
	v_add_u32_e32 v29, v10, v11
	v_add_u32_e32 v30, v10, v12
	v_add_u32_e32 v31, v10, v14
	v_cmp_ne_u32_e64 s[4:5], 1, v16
	s_mov_b64 s[4:5], -1
	v_add_u32_e32 v32, v10, v13
	v_add_u32_e32 v33, v10, v15
	s_mov_b32 s29, s2
	s_branch .LBB0_10

; #define LAS __attribute__((address_space(3)))
; __device__ __forceinline__ unsigned pk2(float lo, float hi) { const f32x2 v = {lo, hi}; return __builtin_bit_cast(unsigned, __builtin_convertvector(v, hbf2)); }
; __device__ __forceinline__ void tr_item(const float* __restrict__ W, int K, int Nsrc, int col0, int nvalid, const float* __restrict__ gain, bf16_t* WT, int drow0, int k0, LAS float* scr, int lane) {
;     ...
;     const int c = lane & 7;
; #pragma unroll
;     for (int j = 0; j < 4; ++j) { const int n = (lane >> 3) + 8 * j; const LAS float* s = scr + (8 * c) * 33 + n;
;         u32x4 o; o.x = pk2(s[0 * 33], s[1 * 33]); o.y = pk2(s[2 * 33], s[3 * 33]); o.z = pk2(s[4 * 33], s[5 * 33]); o.w = pk2(s[6 * 33], s[7 * 33]);
;         *(u32x4*)(WT + (size_t)(drow0 + n) * K + k0 + 8 * c) = o; }
.LBB0_9:
	s_waitcnt vmcnt(4)
	ds_write2_b32 v14, v12, v13 offset0:172 offset1:238
	ds_read2_b32 v[14:15], v5 offset0:33 offset1:41
	ds_read2_b32 v[16:17], v5 offset1:8
	ds_read2_b32 v[18:19], v5 offset0:66 offset1:74
	ds_read2_b32 v[20:21], v5 offset0:99 offset1:107
	ds_read2_b32 v[22:23], v5 offset0:132 offset1:140
	ds_read2_b32 v[24:25], v5 offset0:165 offset1:173
	ds_read2_b32 v[26:27], v5 offset0:198 offset1:206
	ds_read2_b32 v[38:39], v5 offset0:231 offset1:239
	v_add_u32_e32 v42, s30, v28
	v_ashrrev_i32_e32 v43, 31, v42
	v_lshl_add_u64 v[40:41], s[6:7], 1, v[8:9]
	v_lshlrev_b64 v[44:45], 12, v[42:43]
	s_waitcnt vmcnt(1) lgkmcnt(6)
	v_mul_f32_e32 v16, v16, v144
	v_mul_f32_e32 v14, v14, v145
	v_cvt_pk_bf16_f32 v10, v16, v14
	s_waitcnt vmcnt(0) lgkmcnt(4)
	v_mul_f32_e32 v18, v18, v146
	v_mul_f32_e32 v20, v20, v147
	v_cvt_pk_bf16_f32 v11, v18, v20
	s_waitcnt lgkmcnt(2)
	v_mul_f32_e32 v22, v22, v148
	v_mul_f32_e32 v24, v24, v149
	v_cvt_pk_bf16_f32 v12, v22, v24
	s_waitcnt lgkmcnt(0)
	v_mul_f32_e32 v26, v26, v150
	v_mul_f32_e32 v38, v38, v151
	v_cvt_pk_bf16_f32 v13, v26, v38
	v_lshl_add_u64 v[44:45], v[40:41], 0, v[44:45]
	v_add_u32_e32 v14, 8, v42
	global_store_dwordx4 v[44:45], v[10:13], off
	s_add_i32 s29, s29, s62
	s_add_i32 s3, s3, s25
	v_mul_f32_e32 v17, v17, v144
	v_mul_f32_e32 v15, v15, v145
	v_cvt_pk_bf16_f32 v10, v17, v15
	v_ashrrev_i32_e32 v15, 31, v14
	v_mul_f32_e32 v19, v19, v146
	v_mul_f32_e32 v21, v21, v147
	v_cvt_pk_bf16_f32 v11, v19, v21
	v_mul_f32_e32 v23, v23, v148
	v_mul_f32_e32 v25, v25, v149
	v_cvt_pk_bf16_f32 v12, v23, v25
	v_mul_f32_e32 v27, v27, v150
	v_mul_f32_e32 v39, v39, v151
	v_cvt_pk_bf16_f32 v13, v27, v39
	v_lshlrev_b64 v[14:15], 12, v[14:15]
	ds_read2_b32 v[16:17], v5 offset0:49 offset1:57
	ds_read2_b32 v[18:19], v5 offset0:16 offset1:24
	ds_read2_b32 v[20:21], v5 offset0:82 offset1:90
	ds_read2_b32 v[22:23], v5 offset0:115 offset1:123
	ds_read2_b32 v[24:25], v5 offset0:148 offset1:156
	ds_read2_b32 v[26:27], v5 offset0:181 offset1:189
	ds_read2_b32 v[38:39], v5 offset0:214 offset1:222
	ds_read2_b32 v[44:45], v5 offset0:247 offset1:255
	v_lshl_add_u64 v[14:15], v[40:41], 0, v[14:15]
	global_store_dwordx4 v[14:15], v[10:13], off
	v_add_u32_e32 v14, 16, v42
	v_ashrrev_i32_e32 v15, 31, v14
	v_lshlrev_b64 v[14:15], 12, v[14:15]
	s_waitcnt lgkmcnt(6)
	v_mul_f32_e32 v18, v18, v144
	v_mul_f32_e32 v16, v16, v145
	v_cvt_pk_bf16_f32 v10, v18, v16
	s_waitcnt lgkmcnt(4)
	v_mul_f32_e32 v20, v20, v146
	v_mul_f32_e32 v22, v22, v147
	v_cvt_pk_bf16_f32 v11, v20, v22
	s_waitcnt lgkmcnt(2)
	v_mul_f32_e32 v24, v24, v148
	v_mul_f32_e32 v26, v26, v149
	v_cvt_pk_bf16_f32 v12, v24, v26
	s_waitcnt lgkmcnt(0)
	v_mul_f32_e32 v38, v38, v150
	v_mul_f32_e32 v44, v44, v151
	v_cvt_pk_bf16_f32 v13, v38, v44
	v_lshl_add_u64 v[14:15], v[40:41], 0, v[14:15]
	global_store_dwordx4 v[14:15], v[10:13], off
	v_add_u32_e32 v14, 24, v42
	v_ashrrev_i32_e32 v15, 31, v14
	v_lshlrev_b64 v[14:15], 12, v[14:15]
	s_add_i32 s26, s26, s27
	v_mul_f32_e32 v19, v19, v144
	v_mul_f32_e32 v17, v17, v145
	v_cvt_pk_bf16_f32 v10, v19, v17
	v_mul_f32_e32 v21, v21, v146
	v_mul_f32_e32 v23, v23, v147
	v_cvt_pk_bf16_f32 v11, v21, v23
	v_mul_f32_e32 v25, v25, v148
	v_mul_f32_e32 v27, v27, v149
	v_cvt_pk_bf16_f32 v12, v25, v27
	v_mul_f32_e32 v39, v39, v150
	v_mul_f32_e32 v45, v45, v151
	v_cvt_pk_bf16_f32 v13, v39, v45
	v_lshl_add_u64 v[14:15], v[40:41], 0, v[14:15]
	s_cmpk_lt_i32 s29, 0x2c00
	global_store_dwordx4 v[14:15], v[10:13], off
	s_cbranch_scc0 .LBB0_41
; __device__ __forceinline__ void tr_item(const float* __restrict__ W, int K, int Nsrc, int col0, int nvalid, const float* __restrict__ gain, bf16_t* WT, int drow0, int k0, LAS float* scr, int lane) {
;     ...
;     for (int i = 0; i < 32; ++i) { const int kk = 2 * i + (lane >> 5), n = lane & 31; v[i] = 0.f; if (n < nvalid) v[i] = W[(size_t)(k0 + kk) * Nsrc + col0 + n]; }
; __device__ __forceinline__ void conv_job(int kind, const float* W, const float* W2, int K, int Nsrc, int Ndst, const float* gain, bf16_t* WT, LAS float* scr, int gw, int NGW, int lane) {
;     ...
;     for (int it = gw; it < nitems; it += NGW) {
;         const int kb = it / nb, db = it % nb, d0 = db * 32, k0 = kb * 64; const float* src = W; int col0 = d0, nvalid = 32;
;         if (kind == 1) { const int t = d0 >> 8; int r = d0 & 255; if (r >= 128) { src = W2; r -= 128; } col0 = t * 128 + r; }
;         else if (kind == 2) { if (d0 < 7168) col0 = d0; else if (d0 < 11264) col0 = d0 + 16; else if (d0 == 11264) { col0 = 7168; nvalid = 16; } else { col0 = 0; nvalid = 0; } }
;         tr_item(src, K, Nsrc, col0, nvalid, gain, WT, d0, k0, scr, lane);
.LBB0_10:
	s_mul_hi_i32 s6, s29, 0x2e8ba2e9
	s_lshr_b32 s7, s6, 31
	s_ashr_i32 s6, s6, 6
	s_add_i32 s7, s6, s7
	s_mul_i32 s6, s7, 0xffffd400
	s_add_i32 s30, s3, s6
	s_and_b32 s20, s30, 0xe0
	s_lshl_b32 s6, s7, 6
	s_lshl_b32 s78, s6, 2
	v_add_u32_e32 v152, s78, v153
	global_load_dwordx4 v[144:147], v152, s[8:9]
	global_load_dwordx4 v[148:151], v152, s[8:9] offset:16
	s_add_i32 s21, s20, 0xffffff80
	s_cmpk_gt_u32 s20, 0x7f
	s_mulk_i32 s7, 0xea00
	s_cselect_b32 s31, s1, s11
	s_cselect_b32 s33, s0, s10
	s_add_i32 s7, s26, s7
	s_min_u32 s20, s21, s20
	s_and_b32 s7, s7, 0xffffff80
	s_add_i32 s20, s20, s7
	s_ashr_i32 s21, s20, 31
	s_lshl_b64 s[20:21], s[20:21], 2
	s_add_u32 s20, s33, s20
	v_or_b32_e32 v26, s6, v2
	s_addc_u32 s21, s31, s21
	v_lshl_add_u64 v[10:11], s[20:21], 0, v[6:7]
	v_or_b32_e32 v22, 10, v26
	v_or_b32_e32 v18, 6, v26
	v_mad_i64_i32 v[38:39], s[20:21], v22, s28, v[10:11]
	v_or_b32_e32 v22, 12, v26
	v_mad_i64_i32 v[12:13], s[20:21], v26, s28, v[10:11]
	v_or_b32_e32 v14, 2, v26
	v_or_b32_e32 v16, 4, v26
	v_mad_i64_i32 v[18:19], s[20:21], v18, s28, v[10:11]
	v_or_b32_e32 v20, 8, v26
	v_mad_i64_i32 v[40:41], s[20:21], v22, s28, v[10:11]
	v_or_b32_e32 v22, 14, v26
	v_mad_i64_i32 v[14:15], s[20:21], v14, s28, v[10:11]
	v_mad_i64_i32 v[16:17], s[20:21], v16, s28, v[10:11]
	v_mad_i64_i32 v[20:21], s[20:21], v20, s28, v[10:11]
	v_mad_i64_i32 v[42:43], s[20:21], v22, s28, v[10:11]
	global_load_dword v50, v[12:13], off nt
	global_load_dword v51, v[14:15], off nt
	global_load_dword v24, v[16:17], off nt
	global_load_dword v25, v[18:19], off nt
	global_load_dword v48, v[20:21], off nt
	global_load_dword v49, v[38:39], off nt
	global_load_dword v22, v[40:41], off nt
	global_load_dword v23, v[42:43], off nt
	v_or_b32_e32 v18, 22, v26
	v_mad_i64_i32 v[38:39], s[20:21], v18, s28, v[10:11]
	v_or_b32_e32 v18, 24, v26
	v_mad_i64_i32 v[40:41], s[20:21], v18, s28, v[10:11]
	v_or_b32_e32 v18, 26, v26
	v_or_b32_e32 v12, 16, v26
	v_or_b32_e32 v14, 18, v26
	v_mad_i64_i32 v[42:43], s[20:21], v18, s28, v[10:11]
	v_or_b32_e32 v18, 28, v26
	v_mad_i64_i32 v[12:13], s[20:21], v12, s28, v[10:11]
	v_mad_i64_i32 v[14:15], s[20:21], v14, s28, v[10:11]
	v_or_b32_e32 v16, 20, v26
	v_mad_i64_i32 v[52:53], s[20:21], v18, s28, v[10:11]
	v_or_b32_e32 v18, 30, v26
	v_mad_i64_i32 v[16:17], s[20:21], v16, s28, v[10:11]
	v_mad_i64_i32 v[54:55], s[20:21], v18, s28, v[10:11]
	global_load_dword v46, v[12:13], off nt
	global_load_dword v47, v[14:15], off nt
	global_load_dword v20, v[16:17], off nt
	global_load_dword v21, v[38:39], off nt
	global_load_dword v44, v[40:41], off nt
	global_load_dword v45, v[42:43], off nt
	global_load_dword v18, v[52:53], off nt
	global_load_dword v19, v[54:55], off nt
	v_or_b32_e32 v14, 34, v26
	v_mad_i64_i32 v[38:39], s[20:21], v14, s28, v[10:11]
	v_or_b32_e32 v14, 36, v26
	v_mad_i64_i32 v[52:53], s[20:21], v14, s28, v[10:11]
	v_or_b32_e32 v14, 38, v26
	v_mad_i64_i32 v[54:55], s[20:21], v14, s28, v[10:11]
	v_or_b32_e32 v14, 40, v26
	v_mad_i64_i32 v[56:57], s[20:21], v14, s28, v[10:11]
	v_or_b32_e32 v14, 42, v26
	v_or_b32_e32 v12, 32, v26
	v_mad_i64_i32 v[58:59], s[20:21], v14, s28, v[10:11]
	v_or_b32_e32 v14, 44, v26
	v_mad_i64_i32 v[12:13], s[20:21], v12, s28, v[10:11]
	v_mad_i64_i32 v[60:61], s[20:21], v14, s28, v[10:11]
	v_or_b32_e32 v14, 46, v26
	v_mad_i64_i32 v[62:63], s[20:21], v14, s28, v[10:11]
	global_load_dword v42, v[12:13], off nt
	global_load_dword v43, v[38:39], off nt
	global_load_dword v16, v[52:53], off nt
	global_load_dword v17, v[54:55], off nt
	global_load_dword v40, v[56:57], off nt
	global_load_dword v41, v[58:59], off nt
	global_load_dword v14, v[60:61], off nt
	global_load_dword v15, v[62:63], off nt
	v_or_b32_e32 v12, 48, v26
	v_mad_i64_i32 v[52:53], s[20:21], v12, s28, v[10:11]
	v_or_b32_e32 v12, 50, v26
	v_mad_i64_i32 v[54:55], s[20:21], v12, s28, v[10:11]
	v_or_b32_e32 v12, 52, v26
	v_mad_i64_i32 v[56:57], s[20:21], v12, s28, v[10:11]
	v_or_b32_e32 v12, 54, v26
	v_mad_i64_i32 v[58:59], s[20:21], v12, s28, v[10:11]
	v_or_b32_e32 v12, 56, v26
	v_mad_i64_i32 v[60:61], s[20:21], v12, s28, v[10:11]
	v_or_b32_e32 v12, 58, v26
	v_mad_i64_i32 v[62:63], s[20:21], v12, s28, v[10:11]
	v_or_b32_e32 v12, 60, v26
	v_mad_i64_i32 v[64:65], s[20:21], v12, s28, v[10:11]
	v_or_b32_e32 v12, 62, v26
	v_mad_i64_i32 v[66:67], s[20:21], v12, s28, v[10:11]
	global_load_dword v38, v[52:53], off nt
	global_load_dword v39, v[54:55], off nt
	global_load_dword v12, v[56:57], off nt
	global_load_dword v13, v[58:59], off nt
	global_load_dword v35, v[60:61], off nt
	global_load_dword v37, v[62:63], off nt
	global_load_dword v10, v[64:65], off nt
	global_load_dword v11, v[66:67], off nt
	s_and_b64 vcc, exec, s[4:5]
	s_cbranch_vccnz .LBB0_33
	v_ashrrev_i32_e32 v27, 31, v26
	s_ashr_i32 s7, s6, 31
	v_lshl_add_u64 v[26:27], v[26:27], 2, s[8:9]
	v_lshl_add_u64 v[52:53], s[6:7], 0, v[2:3]
	v_lshl_add_u64 v[52:53], v[52:53], 2, s[8:9]
	global_load_dword v56, v[26:27], off nt
	global_load_dword v57, v[52:53], off offset:8
	global_load_dword v54, v[52:53], off offset:16
	global_load_dword v55, v[52:53], off offset:24
	s_waitcnt vmcnt(3)
	v_mul_f32_e32 v52, v50, v56
	s_waitcnt vmcnt(2)
	v_mul_f32_e32 v53, v51, v57
	ds_write2_b32 v29, v52, v53 offset1:66
	s_waitcnt vmcnt(0)
	v_pk_mul_f32 v[26:27], v[24:25], v[54:55]
	s_cbranch_execnz .LBB0_13

; #define LAS __attribute__((address_space(3)))
; __device__ __forceinline__ void conv_job(int kind, const float* W, const float* W2, int K, int Nsrc, int Ndst, const float* gain, bf16_t* WT, LAS float* scr, int gw, int NGW, int lane) {
;     const int nb = Ndst / 32, nitems = (K / 64) * nb;
;     for (int it = gw; it < nitems; it += NGW) {
;         const int kb = it / nb, db = it % nb, d0 = db * 32, k0 = kb * 64; const float* src = W; int col0 = d0, nvalid = 32;
;         if (kind == 1) { const int t = d0 >> 8; int r = d0 & 255; if (r >= 128) { src = W2; r -= 128; } col0 = t * 128 + r; }
;         else if (kind == 2) { if (d0 < 7168) col0 = d0; else if (d0 < 11264) col0 = d0 + 16; else if (d0 == 11264) { col0 = 7168; nvalid = 16; } else { col0 = 0; nvalid = 0; } }
; __global__ void __launch_bounds__(NTHREADS, 2) mega(Args a) {
;     ...
;         conv_job(2, AIN(I_WIN), nullptr, DM, 11280, NIN, AIN(I_MIXN), (bf16_t*)(ws + WS_WIN), scr, gw, NGW, lane);
.LBB0_44:
	s_cmpk_gt_i32 s2, 0x2cff
	s_cbranch_scc1 .LBB0_183
	s_load_dwordx4 s[8:11], s[18:19], 0x30
	v_and_b32_e32 v3, 56, v36
	v_lshlrev_b32_e32 v153, 2, v3
	v_lshlrev_b32_e32 v8, 2, v4
	v_lshlrev_b32_e32 v10, 1, v3
	v_mov_b32_e32 v11, 0
	v_mul_u32_u24_e32 v12, 0x84, v2
	v_add_u32_e32 v13, s24, v8
	s_waitcnt lgkmcnt(0)
	s_cmp_lg_u64 s[8:9], 0
	v_mul_u32_u24_e32 v5, 0x84, v3
	v_lshl_add_u64 v[6:7], s[14:15], 0, v[10:11]
	s_mov_b64 s[4:5], 0x6600000
	v_lshlrev_b32_e32 v3, 2, v28
	v_mov_b32_e32 v9, v11
	s_cselect_b64 s[0:1], -1, 0
	s_mov_b64 s[0:1], 0
	v_lshl_add_u64 v[6:7], v[6:7], 0, s[4:5]
	v_add3_u32 v5, s24, v5, v3
	v_cmp_gt_u32_e64 s[4:5], 16, v4
	v_lshl_add_u64 v[8:9], s[10:11], 0, v[8:9]
	v_mov_b32_e32 v3, v11
	s_lshl_b32 s3, s2, 5
	s_lshl_b32 s25, s62, 5
	s_mov_b32 s26, 0xb040
	v_add_u32_e32 v14, v13, v12
	s_mov_b32 s27, s2
	s_branch .LBB0_48

; #define LAS __attribute__((address_space(3)))
; __device__ __forceinline__ unsigned pk2(float lo, float hi) { const f32x2 v = {lo, hi}; return __builtin_bit_cast(unsigned, __builtin_convertvector(v, hbf2)); }
; __device__ __forceinline__ void tr_item(const float* __restrict__ W, int K, int Nsrc, int col0, int nvalid, const float* __restrict__ gain, bf16_t* WT, int drow0, int k0, LAS float* scr, int lane) {
;     ...
;     const int c = lane & 7;
; #pragma unroll
;     for (int j = 0; j < 4; ++j) { const int n = (lane >> 3) + 8 * j; const LAS float* s = scr + (8 * c) * 33 + n;
;         u32x4 o; o.x = pk2(s[0 * 33], s[1 * 33]); o.y = pk2(s[2 * 33], s[3 * 33]); o.z = pk2(s[4 * 33], s[5 * 33]); o.w = pk2(s[6 * 33], s[7 * 33]);
;         *(u32x4*)(WT + (size_t)(drow0 + n) * K + k0 + 8 * c) = o; }
.LBB0_47:
	ds_write_b32 v14, v10 offset:8184
	ds_read2_b32 v[16:17], v5 offset0:33 offset1:41
	ds_read2_b32 v[18:19], v5 offset1:8
	ds_read2_b32 v[20:21], v5 offset0:66 offset1:74
	ds_read2_b32 v[22:23], v5 offset0:99 offset1:107
	ds_read2_b32 v[24:25], v5 offset0:132 offset1:140
	ds_read2_b32 v[30:31], v5 offset0:165 offset1:173
	ds_read2_b32 v[32:33], v5 offset0:198 offset1:206
	ds_read2_b32 v[38:39], v5 offset0:231 offset1:239
	s_add_i32 s6, s3, s28
	v_add_u32_e32 v42, s6, v28
	v_ashrrev_i32_e32 v43, 31, v42
	v_lshl_add_u64 v[40:41], s[10:11], 1, v[6:7]
	v_lshlrev_b64 v[44:45], 12, v[42:43]
	s_waitcnt lgkmcnt(6)
	v_mul_f32_e32 v18, v18, v144
	v_mul_f32_e32 v16, v16, v145
	v_cvt_pk_bf16_f32 v10, v18, v16
	s_waitcnt lgkmcnt(4)
	v_mul_f32_e32 v20, v20, v146
	v_mul_f32_e32 v22, v22, v147
	v_cvt_pk_bf16_f32 v11, v20, v22
	s_waitcnt lgkmcnt(2)
	v_mul_f32_e32 v24, v24, v148
	v_mul_f32_e32 v30, v30, v149
	v_cvt_pk_bf16_f32 v12, v24, v30
	s_waitcnt lgkmcnt(0)
	v_mul_f32_e32 v32, v32, v150
	v_mul_f32_e32 v38, v38, v151
	v_cvt_pk_bf16_f32 v13, v32, v38
	v_lshl_add_u64 v[44:45], v[40:41], 0, v[44:45]
	v_add_u32_e32 v16, 8, v42
	global_store_dwordx4 v[44:45], v[10:13], off
	s_add_i32 s27, s27, s62
	s_add_i32 s3, s3, s25
	v_mul_f32_e32 v19, v19, v144
	v_mul_f32_e32 v17, v17, v145
	v_cvt_pk_bf16_f32 v10, v19, v17
	v_ashrrev_i32_e32 v17, 31, v16
	v_mul_f32_e32 v21, v21, v146
	v_mul_f32_e32 v23, v23, v147
	v_cvt_pk_bf16_f32 v11, v21, v23
	v_mul_f32_e32 v25, v25, v148
	v_mul_f32_e32 v31, v31, v149
	v_cvt_pk_bf16_f32 v12, v25, v31
	v_mul_f32_e32 v33, v33, v150
	v_mul_f32_e32 v39, v39, v151
	v_cvt_pk_bf16_f32 v13, v33, v39
	v_lshlrev_b64 v[16:17], 12, v[16:17]
	ds_read2_b32 v[18:19], v5 offset0:49 offset1:57
	ds_read2_b32 v[20:21], v5 offset0:16 offset1:24
	ds_read2_b32 v[22:23], v5 offset0:82 offset1:90
	ds_read2_b32 v[24:25], v5 offset0:115 offset1:123
	ds_read2_b32 v[30:31], v5 offset0:148 offset1:156
	ds_read2_b32 v[32:33], v5 offset0:181 offset1:189
	ds_read2_b32 v[38:39], v5 offset0:214 offset1:222
	ds_read2_b32 v[44:45], v5 offset0:247 offset1:255
	v_lshl_add_u64 v[16:17], v[40:41], 0, v[16:17]
	global_store_dwordx4 v[16:17], v[10:13], off
	v_add_u32_e32 v16, 16, v42
	v_ashrrev_i32_e32 v17, 31, v16
	v_lshlrev_b64 v[16:17], 12, v[16:17]
	s_waitcnt lgkmcnt(6)
	v_mul_f32_e32 v20, v20, v144
	v_mul_f32_e32 v18, v18, v145
	v_cvt_pk_bf16_f32 v10, v20, v18
	s_waitcnt lgkmcnt(4)
	v_mul_f32_e32 v22, v22, v146
	v_mul_f32_e32 v24, v24, v147
	v_cvt_pk_bf16_f32 v11, v22, v24
	s_waitcnt lgkmcnt(2)
	v_mul_f32_e32 v30, v30, v148
	v_mul_f32_e32 v32, v32, v149
	v_cvt_pk_bf16_f32 v12, v30, v32
	s_waitcnt lgkmcnt(0)
	v_mul_f32_e32 v38, v38, v150
	v_mul_f32_e32 v44, v44, v151
	v_cvt_pk_bf16_f32 v13, v38, v44
	v_lshl_add_u64 v[16:17], v[40:41], 0, v[16:17]
	global_store_dwordx4 v[16:17], v[10:13], off
	v_add_u32_e32 v16, 24, v42
	v_ashrrev_i32_e32 v17, 31, v16
	v_lshlrev_b64 v[16:17], 12, v[16:17]
	v_mul_f32_e32 v21, v21, v144
	v_mul_f32_e32 v19, v19, v145
	v_cvt_pk_bf16_f32 v10, v21, v19
	v_mul_f32_e32 v23, v23, v146
	v_mul_f32_e32 v25, v25, v147
	v_cvt_pk_bf16_f32 v11, v23, v25
	v_mul_f32_e32 v31, v31, v148
	v_mul_f32_e32 v33, v33, v149
	v_cvt_pk_bf16_f32 v12, v31, v33
	v_mul_f32_e32 v39, v39, v150
	v_mul_f32_e32 v45, v45, v151
	v_cvt_pk_bf16_f32 v13, v39, v45
	v_lshl_add_u64 v[16:17], v[40:41], 0, v[16:17]
	s_cmpk_lt_i32 s27, 0x2d00
	global_store_dwordx4 v[16:17], v[10:13], off
	s_cbranch_scc0 .LBB0_183

; __device__ __forceinline__ void tr_item(const float* __restrict__ W, int K, int Nsrc, int col0, int nvalid, const float* __restrict__ gain, bf16_t* WT, int drow0, int k0, LAS float* scr, int lane) {
;     ...
;     for (int i = 0; i < 32; ++i) { const int kk = 2 * i + (lane >> 5), n = lane & 31; v[i] = 0.f; if (n < nvalid) v[i] = W[(size_t)(k0 + kk) * Nsrc + col0 + n]; }
; __device__ __forceinline__ void conv_job(int kind, const float* W, const float* W2, int K, int Nsrc, int Ndst, const float* gain, bf16_t* WT, LAS float* scr, int gw, int NGW, int lane) {
;     ...
;         const int kb = it / nb, db = it % nb, d0 = db * 32, k0 = kb * 64; const float* src = W; int col0 = d0, nvalid = 32;
;         if (kind == 1) { const int t = d0 >> 8; int r = d0 & 255; if (r >= 128) { src = W2; r -= 128; } col0 = t * 128 + r; }
;         else if (kind == 2) { if (d0 < 7168) col0 = d0; else if (d0 < 11264) col0 = d0 + 16; else if (d0 == 11264) { col0 = 7168; nvalid = 16; } else { col0 = 0; nvalid = 0; } }
.LBB0_54:
	s_lshl_b32 s10, s21, 6
	s_lshl_b32 s78, s10, 2
	v_add_u32_e32 v152, s78, v153
	global_load_dwordx4 v[144:147], v152, s[8:9]
	global_load_dwordx4 v[148:151], v152, s[8:9] offset:16
	s_ashr_i32 s21, s20, 31
	v_or_b32_e32 v10, s10, v2
	v_lshl_add_u64 v[12:13], s[20:21], 2, v[8:9]
	v_mov_b32_e32 v47, 0
	v_mov_b32_e32 v50, 0
	s_and_saveexec_b64 s[20:21], s[6:7]
	s_cbranch_execz .LBB0_56
	v_mad_i64_i32 v[16:17], s[30:31], v10, s26, v[12:13]
	global_load_dword v50, v[16:17], off nt

; #define LAS __attribute__((address_space(3)))
; __device__ __forceinline__ void conv_job(int kind, const float* W, const float* W2, int K, int Nsrc, int Ndst, const float* gain, bf16_t* WT, LAS float* scr, int gw, int NGW, int lane) {
;     const int nb = Ndst / 32, nitems = (K / 64) * nb;
;     for (int it = gw; it < nitems; it += NGW) {
; __device__ __forceinline__ void gemm_range(const Args& a, LAS unsigned char* lds, int lo, int hi, int first, int last, int G, int bx, int NGW, const XcdBarrier& xbar) {
;     ...
;         if (ph == P_XQ) {
;             LAS float* scr = (LAS float*)(lds + wave * 8704);
;             conv_job(1, AIN(I_F2G), AIN(I_F2U), DM, FF, NGU, AIN(I_F2N), (bf16_t*)(ws + WS_WGU), scr, gw, NGW, lane);
;             conv_job(0, AIN(I_F2D), nullptr, FF, DM, DM, nullptr, (bf16_t*)(ws + WS_WD), scr, gw, NGW, lane);
;         }
.LBB0_1647:
	v_readlane_b32 s0, v253, 40
	v_readlane_b32 s1, v253, 41
	s_and_b64 vcc, exec, s[0:1]
	v_readlane_b32 s62, v253, 11
	v_readlane_b32 s63, v253, 12
	s_cbranch_vccz .LBB0_1670
	v_readlane_b32 s0, v253, 52
	s_ashr_i32 s0, s0, 6
	v_readlane_b32 s1, v252, 19
	s_add_i32 s2, s0, s1
	s_movk_i32 s36, 0x2c00
	s_movk_i32 s37, 0x1600
	s_mov_b32 s38, 0
	s_cmpk_lg_u32 s62, 0x800
	s_cbranch_scc1 .Lxq_rebal_done
	s_cmpk_lt_u32 s2, 0x480
	s_cbranch_scc1 .Lxq_rebal_busy
	s_addk_i32 s2, 0xfb80
	s_movk_i32 s62, 0x380
	s_movk_i32 s36, 9856
	s_movk_i32 s37, 4928
	s_branch .Lxq_rebal_done
.Lxq_rebal_busy:
	s_addk_i32 s2, 9856
	s_movk_i32 s62, 0x480
	s_movk_i32 s38, 60608
.Lxq_rebal_done:
	s_mulk_i32 s0, 0x2200
	s_add_i32 s3, s0, 0
	v_readlane_b32 s0, v253, 50
	v_readlane_b32 s1, v253, 51
	s_lshl_b64 s[0:1], s[0:1], 3
	v_readlane_b32 s4, v253, 0
	v_readlane_b32 s5, v253, 1
	s_add_u32 s0, s4, s0
	s_addc_u32 s1, s5, s1
	v_lshrrev_b32_e32 v2, 5, v236
	v_lshrrev_b32_e32 v27, 3, v236
	v_lshlrev_b32_e32 v0, 3, v236
	s_cmp_ge_i32 s2, s36
	v_mul_u32_u24_e32 v26, 0x84, v2
	v_and_b32_e32 v29, 56, v0
	v_lshlrev_b32_e32 v153, 2, v29
	v_lshlrev_b32_e32 v28, 2, v27
	s_cbranch_scc1 .LBB0_1667
	s_load_dwordx4 s[44:47], s[0:1], 0xa8
	s_load_dwordx2 s[4:5], s[0:1], 0xb8
	v_and_b32_e32 v6, 31, v235
	s_movk_i32 s8, 0x84
	v_lshlrev_b32_e32 v0, 1, v29
	v_mad_u32_u24 v7, v2, s8, v232
	v_lshl_add_u32 v8, v6, 2, s3
	s_waitcnt lgkmcnt(0)
	s_cmp_lg_u64 s[44:45], 0
	v_mad_u32_u24 v9, v2, s8, v233
	v_mul_u32_u24_e32 v3, 0x84, v29
	v_lshl_add_u64 v[4:5], s[92:93], 0, v[0:1]
	s_mov_b64 s[8:9], 0x14300000
	s_cselect_b64 s[6:7], -1, 0
	s_mov_b64 s[6:7], 0
	v_lshl_add_u64 v[4:5], v[4:5], 0, s[8:9]
	v_add3_u32 v30, s3, v3, v28
	v_mov_b32_e32 v3, v1
	s_lshl_b32 s12, s2, 5
	s_lshl_b32 s13, s62, 5
	s_lshl_b32 s14, s2, 4
	s_lshl_b32 s15, s62, 4
	v_lshlrev_b32_e32 v0, 2, v6
	v_add_u32_e32 v31, v8, v7
	v_add_u32_e32 v32, v8, v26
	v_add_u32_e32 v33, v8, v9
	s_mov_b32 s16, s2
	s_branch .LBB0_1652

; #define LAS __attribute__((address_space(3)))
; __device__ __forceinline__ unsigned pk2(float lo, float hi) { const f32x2 v = {lo, hi}; return __builtin_bit_cast(unsigned, __builtin_convertvector(v, hbf2)); }
; __device__ __forceinline__ void tr_item(const float* __restrict__ W, int K, int Nsrc, int col0, int nvalid, const float* __restrict__ gain, bf16_t* WT, int drow0, int k0, LAS float* scr, int lane) {
;     ...
;     const int c = lane & 7;
; #pragma unroll
;     for (int j = 0; j < 4; ++j) { const int n = (lane >> 3) + 8 * j; const LAS float* s = scr + (8 * c) * 33 + n;
;         u32x4 o; o.x = pk2(s[0 * 33], s[1 * 33]); o.y = pk2(s[2 * 33], s[3 * 33]); o.z = pk2(s[4 * 33], s[5 * 33]); o.w = pk2(s[6 * 33], s[7 * 33]);
;         *(u32x4*)(WT + (size_t)(drow0 + n) * K + k0 + 8 * c) = o; }
.LBB0_1651:
	s_waitcnt vmcnt(3)
	v_add_u32_e32 v6, 0x1400, v33
	ds_write2_b32 v6, v10, v11 offset0:40 offset1:106
	ds_write2_b32 v6, v12, v13 offset0:172 offset1:238
	ds_read2_b32 v[12:13], v30 offset0:33 offset1:41
	ds_read2_b32 v[14:15], v30 offset1:8
	ds_read2_b32 v[16:17], v30 offset0:66 offset1:74
	ds_read2_b32 v[18:19], v30 offset0:99 offset1:107
	ds_read2_b32 v[20:21], v30 offset0:132 offset1:140
	ds_read2_b32 v[22:23], v30 offset0:165 offset1:173
	ds_read2_b32 v[24:25], v30 offset0:198 offset1:206
	ds_read2_b32 v[34:35], v30 offset0:231 offset1:239
	v_add_u32_e32 v36, s17, v27
	v_ashrrev_i32_e32 v37, 31, v36
	v_lshl_add_u64 v[10:11], s[8:9], 1, v[4:5]
	v_lshlrev_b64 v[38:39], 12, v[36:37]
	s_waitcnt lgkmcnt(6)
	v_mul_f32_e32 v14, v14, v144
	v_mul_f32_e32 v12, v12, v145
	v_cvt_pk_bf16_f32 v6, v14, v12
	s_waitcnt vmcnt(2) lgkmcnt(4)
	v_mul_f32_e32 v16, v16, v146
	v_mul_f32_e32 v18, v18, v147
	v_cvt_pk_bf16_f32 v7, v16, v18
	s_waitcnt vmcnt(1) lgkmcnt(2)
	v_mul_f32_e32 v20, v20, v148
	v_mul_f32_e32 v22, v22, v149
	v_cvt_pk_bf16_f32 v8, v20, v22
	s_waitcnt vmcnt(0) lgkmcnt(0)
	v_mul_f32_e32 v24, v24, v150
	v_mul_f32_e32 v34, v34, v151
	v_cvt_pk_bf16_f32 v9, v24, v34
	v_lshl_add_u64 v[38:39], v[10:11], 0, v[38:39]
	v_add_u32_e32 v12, 8, v36
	global_store_dwordx4 v[38:39], v[6:9], off
	v_add_u32_e32 v38, 16, v36
	v_ashrrev_i32_e32 v39, 31, v38
	v_mul_f32_e32 v15, v15, v144
	v_mul_f32_e32 v13, v13, v145
	v_cvt_pk_bf16_f32 v6, v15, v13
	v_ashrrev_i32_e32 v13, 31, v12
	v_lshlrev_b64 v[12:13], 12, v[12:13]
	v_mul_f32_e32 v17, v17, v146
	v_mul_f32_e32 v19, v19, v147
	v_cvt_pk_bf16_f32 v7, v17, v19
	v_mul_f32_e32 v21, v21, v148
	v_mul_f32_e32 v23, v23, v149
	v_cvt_pk_bf16_f32 v8, v21, v23
	v_mul_f32_e32 v25, v25, v150
	v_mul_f32_e32 v35, v35, v151
	v_cvt_pk_bf16_f32 v9, v25, v35
	v_lshl_add_u64 v[12:13], v[10:11], 0, v[12:13]
	global_store_dwordx4 v[12:13], v[6:9], off
	ds_read2_b32 v[12:13], v30 offset0:49 offset1:57
	ds_read2_b32 v[14:15], v30 offset0:16 offset1:24
	ds_read2_b32 v[16:17], v30 offset0:82 offset1:90
	ds_read2_b32 v[18:19], v30 offset0:115 offset1:123
	ds_read2_b32 v[20:21], v30 offset0:148 offset1:156
	ds_read2_b32 v[22:23], v30 offset0:181 offset1:189
	ds_read2_b32 v[24:25], v30 offset0:214 offset1:222
	ds_read2_b32 v[34:35], v30 offset0:247 offset1:255
	v_lshlrev_b64 v[38:39], 12, v[38:39]
	s_waitcnt lgkmcnt(6)
	v_mul_f32_e32 v14, v14, v144
	v_mul_f32_e32 v12, v12, v145
	v_cvt_pk_bf16_f32 v6, v14, v12
	s_waitcnt lgkmcnt(4)
	v_mul_f32_e32 v16, v16, v146
	v_mul_f32_e32 v18, v18, v147
	v_cvt_pk_bf16_f32 v7, v16, v18
	s_waitcnt lgkmcnt(2)
	v_mul_f32_e32 v20, v20, v148
	v_mul_f32_e32 v22, v22, v149
	v_cvt_pk_bf16_f32 v8, v20, v22
	s_waitcnt lgkmcnt(0)
	v_mul_f32_e32 v24, v24, v150
	v_mul_f32_e32 v34, v34, v151
	v_cvt_pk_bf16_f32 v9, v24, v34
	v_lshl_add_u64 v[38:39], v[10:11], 0, v[38:39]
	v_add_u32_e32 v12, 24, v36
	global_store_dwordx4 v[38:39], v[6:9], off
	s_add_i32 s16, s16, s62
	s_add_i32 s12, s12, s13
	v_mul_f32_e32 v15, v15, v144
	v_mul_f32_e32 v13, v13, v145
	v_cvt_pk_bf16_f32 v6, v15, v13
	v_ashrrev_i32_e32 v13, 31, v12
	v_lshlrev_b64 v[12:13], 12, v[12:13]
	s_add_i32 s14, s14, s15
	v_mul_f32_e32 v17, v17, v146
	v_mul_f32_e32 v19, v19, v147
	v_cvt_pk_bf16_f32 v7, v17, v19
	v_mul_f32_e32 v21, v21, v148
	v_mul_f32_e32 v23, v23, v149
	v_cvt_pk_bf16_f32 v8, v21, v23
	v_mul_f32_e32 v25, v25, v150
	v_mul_f32_e32 v35, v35, v151
	v_cvt_pk_bf16_f32 v9, v25, v35
	v_lshl_add_u64 v[10:11], v[10:11], 0, v[12:13]
	s_cmp_lt_i32 s16, s36
	global_store_dwordx4 v[10:11], v[6:9], off
	s_cbranch_scc0 .LBB0_1667
; __device__ __forceinline__ void tr_item(const float* __restrict__ W, int K, int Nsrc, int col0, int nvalid, const float* __restrict__ gain, bf16_t* WT, int drow0, int k0, LAS float* scr, int lane) {
;     ...
;     for (int i = 0; i < 32; ++i) { const int kk = 2 * i + (lane >> 5), n = lane & 31; v[i] = 0.f; if (n < nvalid) v[i] = W[(size_t)(k0 + kk) * Nsrc + col0 + n]; }
; __device__ __forceinline__ void conv_job(int kind, const float* W, const float* W2, int K, int Nsrc, int Ndst, const float* gain, bf16_t* WT, LAS float* scr, int gw, int NGW, int lane) {
;     ...
;         const int kb = it / nb, db = it % nb, d0 = db * 32, k0 = kb * 64; const float* src = W; int col0 = d0, nvalid = 32;
;         if (kind == 1) { const int t = d0 >> 8; int r = d0 & 255; if (r >= 128) { src = W2; r -= 128; } col0 = t * 128 + r; }
;         else if (kind == 2) { if (d0 < 7168) col0 = d0; else if (d0 < 11264) col0 = d0 + 16; else if (d0 == 11264) { col0 = 7168; nvalid = 16; } else { col0 = 0; nvalid = 0; } }
;         tr_item(src, K, Nsrc, col0, nvalid, gain, WT, d0, k0, scr, lane);
.LBB0_1652:
	s_mul_hi_i32 s8, s16, 0x2e8ba2e9
	s_lshr_b32 s9, s8, 31
	s_ashr_i32 s8, s8, 6
	s_add_i32 s9, s8, s9
	s_mul_i32 s8, s9, 0xffffd400
	s_add_i32 s17, s12, s8
	s_and_b32 s10, s17, 0xe0
	s_lshl_b32 s8, s9, 6
	s_lshl_b32 s78, s8, 2
	v_add_u32_e32 v152, s78, v153
	global_load_dwordx4 v[144:147], v152, s[44:45]
	global_load_dwordx4 v[148:151], v152, s[44:45] offset:16
	s_add_i32 s11, s10, 0xffffff80
	s_cmpk_gt_u32 s10, 0x7f
	s_mulk_i32 s9, 0xea00
	s_cselect_b32 s18, s5, s47
	s_cselect_b32 s19, s4, s46
	s_add_i32 s9, s14, s9
	s_min_u32 s10, s11, s10
	s_and_b32 s9, s9, 0xffffff80
	s_add_i32 s10, s10, s9
	s_ashr_i32 s11, s10, 31
	s_lshl_b64 s[10:11], s[10:11], 2
	s_add_u32 s10, s19, s10
	s_addc_u32 s11, s18, s11
	v_or_b32_e32 v22, s8, v2
	v_lshl_add_u64 v[24:25], s[10:11], 0, v[0:1]
	v_mad_i64_i32 v[6:7], s[10:11], v22, s95, v[24:25]
	global_load_dword v46, v[6:7], off
	v_or_b32_e32 v6, 2, v22
	v_mad_i64_i32 v[6:7], s[10:11], v6, s95, v[24:25]
	global_load_dword v47, v[6:7], off
	v_or_b32_e32 v6, 4, v22
	v_mad_i64_i32 v[6:7], s[10:11], v6, s95, v[24:25]
	global_load_dword v48, v[6:7], off
	v_or_b32_e32 v6, 6, v22
	v_mad_i64_i32 v[6:7], s[10:11], v6, s95, v[24:25]
	global_load_dword v49, v[6:7], off
	v_or_b32_e32 v6, 8, v22
	v_mad_i64_i32 v[6:7], s[10:11], v6, s95, v[24:25]
	global_load_dword v18, v[6:7], off
	v_or_b32_e32 v6, 10, v22
	v_mad_i64_i32 v[6:7], s[10:11], v6, s95, v[24:25]
	global_load_dword v19, v[6:7], off
	v_or_b32_e32 v6, 12, v22
	v_mad_i64_i32 v[6:7], s[10:11], v6, s95, v[24:25]
	global_load_dword v20, v[6:7], off
	v_or_b32_e32 v6, 14, v22
	v_mad_i64_i32 v[6:7], s[10:11], v6, s95, v[24:25]
	global_load_dword v21, v[6:7], off
	v_or_b32_e32 v6, 16, v22
	v_mad_i64_i32 v[6:7], s[10:11], v6, s95, v[24:25]
	global_load_dword v42, v[6:7], off
	v_or_b32_e32 v6, 18, v22
	v_mad_i64_i32 v[6:7], s[10:11], v6, s95, v[24:25]
	global_load_dword v43, v[6:7], off
	v_or_b32_e32 v6, 20, v22
	v_mad_i64_i32 v[6:7], s[10:11], v6, s95, v[24:25]
	global_load_dword v44, v[6:7], off
	v_or_b32_e32 v6, 22, v22
	v_mad_i64_i32 v[6:7], s[10:11], v6, s95, v[24:25]
	global_load_dword v45, v[6:7], off
	v_or_b32_e32 v6, 24, v22
	v_mad_i64_i32 v[6:7], s[10:11], v6, s95, v[24:25]
	global_load_dword v14, v[6:7], off
	v_or_b32_e32 v6, 26, v22
	v_mad_i64_i32 v[6:7], s[10:11], v6, s95, v[24:25]
	global_load_dword v15, v[6:7], off
	v_or_b32_e32 v6, 28, v22
	v_mad_i64_i32 v[6:7], s[10:11], v6, s95, v[24:25]
	global_load_dword v16, v[6:7], off
	v_or_b32_e32 v6, 30, v22
	v_mad_i64_i32 v[6:7], s[10:11], v6, s95, v[24:25]
	global_load_dword v17, v[6:7], off
	v_or_b32_e32 v6, 32, v22
	v_mad_i64_i32 v[6:7], s[10:11], v6, s95, v[24:25]
	global_load_dword v38, v[6:7], off
	v_or_b32_e32 v6, 34, v22
	v_mad_i64_i32 v[6:7], s[10:11], v6, s95, v[24:25]
	global_load_dword v39, v[6:7], off
	v_or_b32_e32 v6, 36, v22
	v_mad_i64_i32 v[6:7], s[10:11], v6, s95, v[24:25]
	global_load_dword v40, v[6:7], off
	v_or_b32_e32 v6, 38, v22
	v_mad_i64_i32 v[6:7], s[10:11], v6, s95, v[24:25]
	global_load_dword v41, v[6:7], off
	v_or_b32_e32 v6, 40, v22
	v_mad_i64_i32 v[6:7], s[10:11], v6, s95, v[24:25]
	global_load_dword v10, v[6:7], off
	v_or_b32_e32 v6, 42, v22
	v_mad_i64_i32 v[6:7], s[10:11], v6, s95, v[24:25]
	global_load_dword v11, v[6:7], off
	v_or_b32_e32 v6, 44, v22
	v_mad_i64_i32 v[6:7], s[10:11], v6, s95, v[24:25]
	global_load_dword v12, v[6:7], off
	v_or_b32_e32 v6, 46, v22
	v_mad_i64_i32 v[6:7], s[10:11], v6, s95, v[24:25]
	global_load_dword v13, v[6:7], off
	v_or_b32_e32 v6, 48, v22
	v_mad_i64_i32 v[6:7], s[10:11], v6, s95, v[24:25]
	global_load_dword v34, v[6:7], off
	v_or_b32_e32 v6, 50, v22
	v_mad_i64_i32 v[6:7], s[10:11], v6, s95, v[24:25]
	global_load_dword v35, v[6:7], off
	v_or_b32_e32 v6, 52, v22
	v_mad_i64_i32 v[6:7], s[10:11], v6, s95, v[24:25]
	global_load_dword v36, v[6:7], off
	v_or_b32_e32 v6, 54, v22
	v_mad_i64_i32 v[6:7], s[10:11], v6, s95, v[24:25]
	global_load_dword v37, v[6:7], off
	v_or_b32_e32 v6, 56, v22
	v_mad_i64_i32 v[6:7], s[10:11], v6, s95, v[24:25]
	global_load_dword v6, v[6:7], off
	v_or_b32_e32 v7, 58, v22
	v_mad_i64_i32 v[8:9], s[10:11], v7, s95, v[24:25]
	global_load_dword v7, v[8:9], off
	v_or_b32_e32 v8, 60, v22
	v_mad_i64_i32 v[8:9], s[10:11], v8, s95, v[24:25]
	global_load_dword v8, v[8:9], off
	v_or_b32_e32 v9, 62, v22
	v_mad_i64_i32 v[24:25], s[10:11], v9, s95, v[24:25]
	global_load_dword v9, v[24:25], off
	v_cndmask_b32_e64 v23, 0, 1, s[6:7]
	v_cmp_ne_u32_e64 s[40:41], 1, v23
	s_andn2_b64 vcc, exec, s[6:7]
	s_cbranch_vccnz .LBB0_1663
	v_ashrrev_i32_e32 v23, 31, v22
	v_lshl_add_u64 v[22:23], v[22:23], 2, s[44:45]
	global_load_dword v22, v[22:23], off
	s_ashr_i32 s9, s8, 31
	s_waitcnt vmcnt(0)
	v_mul_f32_e32 v50, v46, v22
	v_lshl_add_u64 v[22:23], s[8:9], 0, v[2:3]
	v_lshl_add_u64 v[24:25], v[22:23], 2, s[44:45]
	global_load_dword v22, v[24:25], off offset:8
	global_load_dword v23, v[24:25], off offset:16
	global_load_dword v51, v[24:25], off offset:24
	s_waitcnt vmcnt(2)
	v_mul_f32_e32 v22, v47, v22
	s_waitcnt vmcnt(1)
	v_mul_f32_e32 v23, v48, v23
	s_waitcnt vmcnt(0)
	v_mul_f32_e32 v51, v49, v51
	ds_write2_b32 v32, v50, v22 offset1:66
	ds_write2_b32 v32, v23, v51 offset0:132 offset1:198
	global_load_dword v22, v[24:25], off offset:32
	global_load_dword v23, v[24:25], off offset:40
	global_load_dword v50, v[24:25], off offset:48
	global_load_dword v51, v[24:25], off offset:56
	s_waitcnt vmcnt(2)
	v_pk_mul_f32 v[22:23], v[18:19], v[22:23]
	s_waitcnt vmcnt(0)
	v_pk_mul_f32 v[24:25], v[20:21], v[50:51]
	s_cbranch_execnz .LBB0_1655

; #define LAS __attribute__((address_space(3)))
; __device__ __forceinline__ void tr_item(const float* __restrict__ W, int K, int Nsrc, int col0, int nvalid, const float* __restrict__ gain, bf16_t* WT, int drow0, int k0, LAS float* scr, int lane) {
;     ...
;     for (int i = 0; i < 32; ++i) { const int kk = 2 * i + (lane >> 5), n = lane & 31; v[i] = 0.f; if (n < nvalid) v[i] = W[(size_t)(k0 + kk) * Nsrc + col0 + n]; }
; __device__ __forceinline__ void conv_job(int kind, const float* W, const float* W2, int K, int Nsrc, int Ndst, const float* gain, bf16_t* WT, LAS float* scr, int gw, int NGW, int lane) {
;     const int nb = Ndst / 32, nitems = (K / 64) * nb;
;     for (int it = gw; it < nitems; it += NGW) {
;         const int kb = it / nb, db = it % nb, d0 = db * 32, k0 = kb * 64; const float* src = W; int col0 = d0, nvalid = 32;
;         if (kind == 1) { const int t = d0 >> 8; int r = d0 & 255; if (r >= 128) { src = W2; r -= 128; } col0 = t * 128 + r; }
;         else if (kind == 2) { if (d0 < 7168) col0 = d0; else if (d0 < 11264) col0 = d0 + 16; else if (d0 == 11264) { col0 = 7168; nvalid = 16; } else { col0 = 0; nvalid = 0; } }
;         tr_item(src, K, Nsrc, col0, nvalid, gain, WT, d0, k0, scr, lane);
.LBB0_1667:
	s_add_i32 s2, s2, s38
	s_cmp_ge_i32 s2, s37
	s_cbranch_scc1 .LBB0_1670
	s_load_dwordx2 s[0:1], s[0:1], 0xc0
	v_and_b32_e32 v6, 0x7c, v234
	v_readlane_b32 s4, v253, 20
	v_mov_b32_e32 v7, v1
	v_add_u32_e32 v8, s3, v6
	v_mul_u32_u24_e32 v3, 0x84, v29
	v_lshlrev_b32_e32 v0, 1, v29
	v_readlane_b32 s5, v253, 21
	s_waitcnt lgkmcnt(0)
	v_lshl_add_u64 v[6:7], s[0:1], 0, v[6:7]
	s_mul_i32 s0, s2, 0x2c000
	v_lshl_add_u64 v[4:5], s[4:5], 0, v[0:1]
	v_add3_u32 v0, s3, v3, v28
	v_mov_b32_e32 v3, s0
	s_movk_i32 s0, 0x1600
	v_mad_u32_u24 v3, v27, s0, v3
	s_lshl_b32 s0, s2, 5
	s_lshl_b32 s1, s62, 5
	v_add_u32_e32 v12, v8, v26
	s_mul_i32 s8, s62, 0x2c000
.LBB0_1669:
	s_ashr_i32 s3, s2, 31
	s_lshr_b32 s3, s3, 26
	s_add_i32 s4, s2, s3
	s_ashr_i32 s3, s4, 6
	s_lshl_b32 s5, s3, 11
	s_andn2_b32 s4, s4, 63
	s_sub_i32 s6, s0, s5
	v_or_b32_e32 v10, s4, v2
	s_ashr_i32 s7, s6, 31
	v_ashrrev_i32_e32 v11, 31, v10
	v_lshl_add_u64 v[8:9], s[6:7], 2, v[6:7]
	v_lshlrev_b64 v[14:15], 13, v[10:11]
	v_lshl_add_u64 v[14:15], v[8:9], 0, v[14:15]
	global_load_dword v13, v[14:15], off
	v_or_b32_e32 v14, 2, v10
	v_or_b32_e32 v16, 4, v10
	v_ashrrev_i32_e32 v15, 31, v14
	v_ashrrev_i32_e32 v17, 31, v16
	v_lshlrev_b64 v[14:15], 13, v[14:15]
	v_lshlrev_b64 v[16:17], 13, v[16:17]
	v_lshl_add_u64 v[14:15], v[8:9], 0, v[14:15]
	v_lshl_add_u64 v[16:17], v[8:9], 0, v[16:17]
	global_load_dword v14, v[14:15], off
	v_or_b32_e32 v18, 8, v10
	global_load_dword v15, v[16:17], off
	v_or_b32_e32 v16, 6, v10
	v_ashrrev_i32_e32 v17, 31, v16
	v_ashrrev_i32_e32 v19, 31, v18
	v_lshlrev_b64 v[16:17], 13, v[16:17]
	v_lshlrev_b64 v[18:19], 13, v[18:19]
	v_lshl_add_u64 v[16:17], v[8:9], 0, v[16:17]
	v_lshl_add_u64 v[18:19], v[8:9], 0, v[18:19]
	global_load_dword v16, v[16:17], off
	v_or_b32_e32 v20, 12, v10
	global_load_dword v17, v[18:19], off
	v_or_b32_e32 v18, 10, v10
	v_ashrrev_i32_e32 v19, 31, v18
	v_ashrrev_i32_e32 v21, 31, v20
	v_lshlrev_b64 v[18:19], 13, v[18:19]
	v_lshlrev_b64 v[20:21], 13, v[20:21]
	v_lshl_add_u64 v[18:19], v[8:9], 0, v[18:19]
	v_lshl_add_u64 v[20:21], v[8:9], 0, v[20:21]
	global_load_dword v18, v[18:19], off
	v_or_b32_e32 v22, 16, v10
	global_load_dword v19, v[20:21], off
	v_or_b32_e32 v20, 14, v10
	v_ashrrev_i32_e32 v21, 31, v20
	v_ashrrev_i32_e32 v23, 31, v22
	v_lshlrev_b64 v[20:21], 13, v[20:21]
	v_lshlrev_b64 v[22:23], 13, v[22:23]
	v_lshl_add_u64 v[20:21], v[8:9], 0, v[20:21]
	v_lshl_add_u64 v[22:23], v[8:9], 0, v[22:23]
	global_load_dword v20, v[20:21], off
	v_or_b32_e32 v24, 20, v10
	global_load_dword v21, v[22:23], off
	v_or_b32_e32 v22, 18, v10
	v_ashrrev_i32_e32 v23, 31, v22
	v_ashrrev_i32_e32 v25, 31, v24
	v_lshlrev_b64 v[22:23], 13, v[22:23]
	v_lshlrev_b64 v[24:25], 13, v[24:25]
	v_lshl_add_u64 v[22:23], v[8:9], 0, v[22:23]
	v_lshl_add_u64 v[24:25], v[8:9], 0, v[24:25]
	global_load_dword v22, v[22:23], off
	v_or_b32_e32 v26, 24, v10
	global_load_dword v23, v[24:25], off
	v_or_b32_e32 v24, 22, v10
	v_ashrrev_i32_e32 v25, 31, v24
	v_ashrrev_i32_e32 v27, 31, v26
	v_lshlrev_b64 v[24:25], 13, v[24:25]
	v_lshlrev_b64 v[26:27], 13, v[26:27]
	v_lshl_add_u64 v[24:25], v[8:9], 0, v[24:25]
	v_lshl_add_u64 v[26:27], v[8:9], 0, v[26:27]
	global_load_dword v24, v[24:25], off
	v_or_b32_e32 v28, 28, v10
	global_load_dword v25, v[26:27], off
	v_or_b32_e32 v26, 26, v10
	v_ashrrev_i32_e32 v27, 31, v26
	v_ashrrev_i32_e32 v29, 31, v28
	v_lshlrev_b64 v[26:27], 13, v[26:27]
	v_lshlrev_b64 v[28:29], 13, v[28:29]
	v_lshl_add_u64 v[26:27], v[8:9], 0, v[26:27]
	v_lshl_add_u64 v[28:29], v[8:9], 0, v[28:29]
	global_load_dword v26, v[26:27], off
	v_or_b32_e32 v30, 32, v10
	global_load_dword v27, v[28:29], off
	v_or_b32_e32 v28, 30, v10
	v_ashrrev_i32_e32 v29, 31, v28
	v_ashrrev_i32_e32 v31, 31, v30
	v_lshlrev_b64 v[28:29], 13, v[28:29]
	v_lshlrev_b64 v[30:31], 13, v[30:31]
	v_lshl_add_u64 v[28:29], v[8:9], 0, v[28:29]
	v_lshl_add_u64 v[30:31], v[8:9], 0, v[30:31]
	global_load_dword v28, v[28:29], off
	v_or_b32_e32 v32, 36, v10
	global_load_dword v29, v[30:31], off
	v_or_b32_e32 v30, 34, v10
	v_ashrrev_i32_e32 v31, 31, v30
	v_ashrrev_i32_e32 v33, 31, v32
	v_lshlrev_b64 v[30:31], 13, v[30:31]
	v_lshlrev_b64 v[32:33], 13, v[32:33]
	v_lshl_add_u64 v[30:31], v[8:9], 0, v[30:31]
	v_lshl_add_u64 v[32:33], v[8:9], 0, v[32:33]
	global_load_dword v30, v[30:31], off
	v_or_b32_e32 v34, 40, v10
	global_load_dword v31, v[32:33], off
	v_or_b32_e32 v32, 38, v10
	v_ashrrev_i32_e32 v33, 31, v32
	v_ashrrev_i32_e32 v35, 31, v34
	v_lshlrev_b64 v[32:33], 13, v[32:33]
	v_lshlrev_b64 v[34:35], 13, v[34:35]
	v_lshl_add_u64 v[32:33], v[8:9], 0, v[32:33]
	v_lshl_add_u64 v[34:35], v[8:9], 0, v[34:35]
	global_load_dword v32, v[32:33], off
	v_or_b32_e32 v36, 44, v10
	global_load_dword v33, v[34:35], off
	v_or_b32_e32 v34, 42, v10
	v_ashrrev_i32_e32 v35, 31, v34
	v_ashrrev_i32_e32 v37, 31, v36
	v_lshlrev_b64 v[34:35], 13, v[34:35]
	v_lshlrev_b64 v[36:37], 13, v[36:37]
	v_lshl_add_u64 v[34:35], v[8:9], 0, v[34:35]
	v_lshl_add_u64 v[36:37], v[8:9], 0, v[36:37]
	global_load_dword v34, v[34:35], off
	v_or_b32_e32 v38, 48, v10
	global_load_dword v35, v[36:37], off
	v_or_b32_e32 v36, 46, v10
	v_ashrrev_i32_e32 v37, 31, v36
	v_ashrrev_i32_e32 v39, 31, v38
	v_lshlrev_b64 v[36:37], 13, v[36:37]
	v_lshlrev_b64 v[38:39], 13, v[38:39]
	v_lshl_add_u64 v[36:37], v[8:9], 0, v[36:37]
	v_lshl_add_u64 v[38:39], v[8:9], 0, v[38:39]
	global_load_dword v36, v[36:37], off
	v_or_b32_e32 v40, 52, v10
	global_load_dword v37, v[38:39], off
	v_or_b32_e32 v38, 50, v10
	v_ashrrev_i32_e32 v39, 31, v38
	v_ashrrev_i32_e32 v41, 31, v40
	v_lshlrev_b64 v[38:39], 13, v[38:39]
	v_lshlrev_b64 v[40:41], 13, v[40:41]
	v_lshl_add_u64 v[38:39], v[8:9], 0, v[38:39]
	v_lshl_add_u64 v[40:41], v[8:9], 0, v[40:41]
	global_load_dword v38, v[38:39], off
	v_or_b32_e32 v42, 56, v10
	global_load_dword v39, v[40:41], off
	v_or_b32_e32 v40, 54, v10
	v_ashrrev_i32_e32 v41, 31, v40
	v_ashrrev_i32_e32 v43, 31, v42
	v_lshlrev_b64 v[40:41], 13, v[40:41]
	v_lshlrev_b64 v[42:43], 13, v[42:43]
	v_lshl_add_u64 v[40:41], v[8:9], 0, v[40:41]
	v_lshl_add_u64 v[42:43], v[8:9], 0, v[42:43]
	global_load_dword v40, v[40:41], off
	v_or_b32_e32 v44, 60, v10
	global_load_dword v41, v[42:43], off
	v_or_b32_e32 v42, 58, v10
	v_ashrrev_i32_e32 v43, 31, v42
	v_or_b32_e32 v10, 62, v10
	v_lshlrev_b64 v[42:43], 13, v[42:43]
	v_ashrrev_i32_e32 v45, 31, v44
	v_ashrrev_i32_e32 v11, 31, v10
	v_lshl_add_u64 v[42:43], v[8:9], 0, v[42:43]
	v_lshlrev_b64 v[44:45], 13, v[44:45]
	v_lshlrev_b64 v[10:11], 13, v[10:11]
	global_load_dword v42, v[42:43], off
	v_lshl_add_u64 v[44:45], v[8:9], 0, v[44:45]
	v_lshl_add_u64 v[8:9], v[8:9], 0, v[10:11]
	global_load_dword v8, v[8:9], off
	v_add_u32_e32 v9, 0x400, v12
	global_load_dword v43, v[44:45], off
	s_waitcnt vmcnt(30)
; #define LAS __attribute__((address_space(3)))
; __device__ __forceinline__ unsigned pk2(float lo, float hi) { const f32x2 v = {lo, hi}; return __builtin_bit_cast(unsigned, __builtin_convertvector(v, hbf2)); }
; #define GRID_SYNC(k) do { if (lo <= (k) && (k) + 1 < hi) { if (hi > 1000) cg::this_grid().sync(); else xcd_barrier(xbar); } } while (0)
; __device__ __forceinline__ void tr_item(const float* __restrict__ W, int K, int Nsrc, int col0, int nvalid, const float* __restrict__ gain, bf16_t* WT, int drow0, int k0, LAS float* scr, int lane) {
;     ...
;     for (int i = 0; i < 32; ++i) { const int kk = 2 * i + (lane >> 5), n = lane & 31; float x = v[i]; if (gain) x *= gain[k0 + kk]; scr[kk * 33 + n] = x; }
;     const int c = lane & 7;
; #pragma unroll
;     for (int j = 0; j < 4; ++j) { const int n = (lane >> 3) + 8 * j; const LAS float* s = scr + (8 * c) * 33 + n;
;         u32x4 o; o.x = pk2(s[0 * 33], s[1 * 33]); o.y = pk2(s[2 * 33], s[3 * 33]); o.z = pk2(s[4 * 33], s[5 * 33]); o.w = pk2(s[6 * 33], s[7 * 33]);
;         *(u32x4*)(WT + (size_t)(drow0 + n) * K + k0 + 8 * c) = o; }
; __device__ __forceinline__ void gemm_range(const Args& a, LAS unsigned char* lds, int lo, int hi, int first, int last, int G, int bx, int NGW, const XcdBarrier& xbar) {
;     ...
;         GRID_SYNC(ph);
	ds_write2_b32 v12, v13, v14 offset1:66
	s_waitcnt vmcnt(28)
	ds_write2_b32 v12, v15, v16 offset0:132 offset1:198
	s_waitcnt vmcnt(26)
	ds_write2_b32 v9, v17, v18 offset0:8 offset1:74
	s_waitcnt vmcnt(24)
	ds_write2_b32 v9, v19, v20 offset0:140 offset1:206
	v_add_u32_e32 v9, 0x800, v12
	s_waitcnt vmcnt(22)
	ds_write2_b32 v9, v21, v22 offset0:16 offset1:82
	s_waitcnt vmcnt(20)
	ds_write2_b32 v9, v23, v24 offset0:148 offset1:214
	v_add_u32_e32 v9, 0xc00, v12
	s_waitcnt vmcnt(18)
	ds_write2_b32 v9, v25, v26 offset0:24 offset1:90
	s_waitcnt vmcnt(16)
	ds_write2_b32 v9, v27, v28 offset0:156 offset1:222
	v_add_u32_e32 v9, 0x1000, v12
	s_waitcnt vmcnt(14)
	ds_write2_b32 v9, v29, v30 offset0:32 offset1:98
	s_waitcnt vmcnt(12)
	ds_write2_b32 v9, v31, v32 offset0:164 offset1:230
	v_add_u32_e32 v9, 0x1400, v12
	s_waitcnt vmcnt(10)
	ds_write2_b32 v9, v33, v34 offset0:40 offset1:106
	s_waitcnt vmcnt(8)
	ds_write2_b32 v9, v35, v36 offset0:172 offset1:238
	v_add_u32_e32 v9, 0x1800, v12
	s_waitcnt vmcnt(6)
	ds_write2_b32 v9, v37, v38 offset0:48 offset1:114
	s_waitcnt vmcnt(4)
	ds_write2_b32 v9, v39, v40 offset0:180 offset1:246
	v_add_u32_e32 v9, 0x1c00, v12
	s_waitcnt vmcnt(2)
	ds_write2_b32 v9, v41, v42 offset0:56 offset1:122
	s_waitcnt vmcnt(0)
	ds_write2_b32 v9, v43, v8 offset0:188 offset1:254
	ds_read2_b32 v[16:17], v0 offset0:33 offset1:41
	ds_read2_b32 v[18:19], v0 offset1:8
	ds_read2_b32 v[20:21], v0 offset0:66 offset1:74
	ds_read2_b32 v[22:23], v0 offset0:99 offset1:107
	ds_read2_b32 v[24:25], v0 offset0:132 offset1:140
	ds_read2_b32 v[26:27], v0 offset0:165 offset1:173
	ds_read2_b32 v[28:29], v0 offset0:198 offset1:206
	ds_read2_b32 v[30:31], v0 offset0:231 offset1:239
	s_mul_i32 s3, s3, 0xff500000
	s_ashr_i32 s5, s4, 31
	v_add_u32_e32 v32, s3, v3
	v_lshl_add_u64 v[14:15], s[4:5], 1, v[4:5]
	v_ashrrev_i32_e32 v33, 31, v32
	s_waitcnt lgkmcnt(6)
	v_cvt_pk_bf16_f32 v8, v18, v16
	s_waitcnt lgkmcnt(4)
	v_cvt_pk_bf16_f32 v9, v20, v22
	s_waitcnt lgkmcnt(2)
	v_cvt_pk_bf16_f32 v10, v24, v26
	s_waitcnt lgkmcnt(0)
	v_cvt_pk_bf16_f32 v11, v28, v30
	v_lshl_add_u64 v[34:35], v[32:33], 1, v[14:15]
	v_add_u32_e32 v16, 0xb000, v32
	global_store_dwordx4 v[34:35], v[8:11], off
	v_add_u32_e32 v34, 0x16000, v32
	v_ashrrev_i32_e32 v35, 31, v34
	v_cvt_pk_bf16_f32 v8, v19, v17
	v_ashrrev_i32_e32 v17, 31, v16
	v_cvt_pk_bf16_f32 v9, v21, v23
	v_cvt_pk_bf16_f32 v10, v25, v27
	v_cvt_pk_bf16_f32 v11, v29, v31
	v_lshl_add_u64 v[16:17], v[16:17], 1, v[14:15]
	global_store_dwordx4 v[16:17], v[8:11], off
	ds_read2_b32 v[16:17], v0 offset0:16 offset1:24
	ds_read2_b32 v[18:19], v0 offset0:49 offset1:57
	ds_read2_b32 v[20:21], v0 offset0:82 offset1:90
	ds_read2_b32 v[22:23], v0 offset0:115 offset1:123
	ds_read2_b32 v[24:25], v0 offset0:148 offset1:156
	ds_read2_b32 v[26:27], v0 offset0:181 offset1:189
	ds_read2_b32 v[28:29], v0 offset0:214 offset1:222
	ds_read2_b32 v[30:31], v0 offset0:247 offset1:255
	v_lshl_add_u64 v[34:35], v[34:35], 1, v[14:15]
	s_waitcnt lgkmcnt(6)
	v_cvt_pk_bf16_f32 v8, v16, v18
	s_waitcnt lgkmcnt(4)
	v_cvt_pk_bf16_f32 v9, v20, v22
	s_waitcnt lgkmcnt(2)
	v_cvt_pk_bf16_f32 v10, v24, v26
	s_waitcnt lgkmcnt(0)
	v_cvt_pk_bf16_f32 v11, v28, v30
	v_add_u32_e32 v16, 0x21000, v32
	global_store_dwordx4 v[34:35], v[8:11], off
	s_add_i32 s2, s2, s62
	s_add_i32 s0, s0, s1
	v_cvt_pk_bf16_f32 v8, v17, v19
	v_ashrrev_i32_e32 v17, 31, v16
	v_cvt_pk_bf16_f32 v9, v21, v23
	v_cvt_pk_bf16_f32 v10, v25, v27
	v_cvt_pk_bf16_f32 v11, v29, v31
	v_lshl_add_u64 v[14:15], v[16:17], 1, v[14:15]
	v_add_u32_e32 v3, s8, v3
	s_cmp_lt_i32 s2, s37
	global_store_dwordx4 v[14:15], v[8:11], off
	s_cbranch_scc1 .LBB0_1669
.LBB0_1670:
	v_readlane_b32 s62, v253, 11
	v_readlane_b32 s0, v253, 14
	s_cmp_le_i32 s0, s21
	v_readlane_b32 s1, v253, 15
	s_cselect_b64 s[4:5], -1, 0
	s_add_i32 s2, s21, 1
	s_cmp_lt_i32 s2, s1
	s_cselect_b64 s[0:1], -1, 0
	s_and_b64 s[4:5], s[4:5], s[0:1]
	s_andn2_b64 vcc, exec, s[4:5]
	s_cbranch_vccnz .LBB0_1405
	v_readlane_b32 s6, v252, 20
	v_readlane_b32 s7, v252, 21
	s_mov_b64 s[4:5], -1
	s_and_b64 vcc, exec, s[6:7]
	s_cbranch_vccz .LBB0_1725
	s_waitcnt vmcnt(0)
	s_barrier
	s_mov_b64 s[4:5], exec
	v_readlane_b32 s6, v253, 9
	v_readlane_b32 s7, v253, 10
	s_and_b64 s[6:7], s[4:5], s[6:7]
	s_mov_b64 exec, s[6:7]
	s_cbranch_execz .LBB0_1724
	v_readlane_b32 s3, v252, 62
	s_waitcnt vmcnt(0) expcnt(0) lgkmcnt(0)
	s_nop 0
	v_mov_b32_e32 v0, s3
	ds_read_b32 v3, v0
	v_readlane_b32 s3, v252, 63
	s_waitcnt lgkmcnt(0)
	v_cmp_ne_u32_e32 vcc, 0, v3
	v_mov_b32_e32 v0, s3
	ds_read_b32 v2, v0
	s_cbranch_vccnz .LBB0_1688
	v_readlane_b32 s8, v253, 2
	v_readlane_b32 s9, v253, 3
	s_load_dwordx2 s[6:7], s[8:9], 0x4
	s_mov_b32 s12, 1
	s_waitcnt lgkmcnt(0)
	s_mul_i32 s3, s6, s69
	s_mul_i32 s3, s3, s7
	s_branch .LBB0_1676
